# K-loop closing s_barrier moved up by one MFMA in all 3 GEMM loops (on top of hoisted vmcnt0)
# speedup vs baseline: 1.0169x; 1.0017x over previous
; #define PG8_STAGE(bufoff, gbase, voff) do { _Pragma("unroll") for (int _i = 0; _i < 2; ++_i) \
;         __builtin_amdgcn_global_load_lds((const unsigned*)((const char*)(gbase) + (voff)[_i]), (PG8_LAS unsigned*)(lds + (bufoff) + ldsw + _i * 8192), 16, 0, 0); } while (0)
; #define PG8_LDA(dst, b, h) do { _Pragma("unroll") for (int m = 0; m < 4; ++m) _Pragma("unroll") for (int k = 0; k < 2; ++k) dst[m][k] = *(const PG8_LAS bf16x8*)(lds + PG8_SA(b, h) + aoff + m * 2048 + k * 1024); } while (0)
; #define PG8_LDB(dst, b, h) do { _Pragma("unroll") for (int n = 0; n < 2; ++n) _Pragma("unroll") for (int k = 0; k < 2; ++k) dst[n][k] = *(const PG8_LAS bf16x8*)(lds + PG8_SB(b, h) + boff + n * 2048 + k * 1024); } while (0)
; #define PG8_MMA(ai, bj, At, Bt) do { __builtin_amdgcn_s_setprio(1); _Pragma("unroll") for (int m = 0; m < 4; ++m) _Pragma("unroll") for (int n = 0; n < 2; ++n) _Pragma("unroll") for (int k = 0; k < 2; ++k) \
;         acc[ai][bj][m][n] = __builtin_amdgcn_mfma_f32_16x16x32_bf16(Bt[n][k], At[m][k], acc[ai][bj][m][n], 0, 0, 0); __builtin_amdgcn_s_setprio(0); } while (0)
; #define PG8_WAIT_V(n) asm volatile("s_waitcnt vmcnt(" #n ")" ::: "memory")
; #define PG8_BAR __builtin_amdgcn_s_barrier()
; template <class Epi, class Sched, bool ALIGN_EPI = false, bool SP2 = false>
; __device__ __forceinline__ void gemm_phase(PG8_LAS unsigned char* lds, const Gemm g, const Sched& S, const Epi& E) {
;     ...
;         for (int t = 0; t < nt; t += 2) {
;             const bool last = (t == nt - 2);
;             const char* a1 = cA + (size_t)(t + 1) * kstep;
;             const char* a2 = last ? nA : cA + (size_t)(t + 2) * kstep; const char* b2 = last ? nB : cB + (size_t)(t + 2) * kstep;
;             const char* a3 = a2 + kstep; const char* b3 = b2 + kstep;
;             if (last && has_next) S.a_ready(nxt);
;             if constexpr (SP2) {
;             PG8_LDB(B0, 0, 0); PG8_LDB(B1, 0, 1); PG8_SCHED; PG8_LDA(At, 0, 0); PG8_STAGE(PG8_SA(1, 1), a1 + hstep, voffA);
;             PG8_WAIT_V(8); PG8_WAIT_L(0); PG8_BAR; PG8_MMA(0, 0, At, B0); PG8_MMA(0, 1, At, B1); PG8_BAR; PG8_SCHED;
;             PG8_LDA(At, 0, 1); PG8_STAGE(PG8_SB(0, 0), b2, voffB); PG8_STAGE(PG8_SB(0, 1), b2 + hstep, voffB); PG8_STAGE(PG8_SA(0, 0), a2, voffA);
;             PG8_WAIT_V(8); PG8_WAIT_L(0); PG8_BAR; PG8_MMA(1, 0, At, B0); PG8_MMA(1, 1, At, B1); PG8_BAR; PG8_SCHED;
.LBB0_213:
	s_add_u32 s12, s10, 0xfff80080
	s_addc_u32 s13, s11, -1
	s_add_i32 s41, 0, 0x10000
	s_cmp_eq_u32 s40, 28
	s_cselect_b32 s15, s16, s13
	s_cselect_b32 s14, s17, s12
	v_add_u32_e32 v0, s41, v196
	s_cselect_b32 s13, s29, s39
	s_cselect_b32 s12, s31, s38
	s_add_i32 s43, 0, 0x14000
	ds_read_b128 v[18:21], v0
	ds_read_b128 v[22:25], v0 offset:1024
	ds_read_b128 v[160:163], v0 offset:2048
	ds_read_b128 v[164:167], v0 offset:3072
	v_add_u32_e32 v0, s43, v196
	ds_read_b128 v[168:171], v0
	ds_read_b128 v[172:175], v0 offset:1024
	ds_read_b128 v[176:179], v0 offset:2048
	ds_read_b128 v[180:183], v0 offset:3072
	v_lshl_add_u64 v[184:185], s[10:11], 0, v[158:159]
	s_add_i32 m0, s61, 0xc000
	ds_read_b128 v[198:201], v197
	ds_read_b128 v[202:205], v197 offset:1024
	ds_read_b128 v[206:209], v197 offset:2048
	ds_read_b128 v[210:213], v197 offset:3072
	ds_read_b128 v[214:217], v197 offset:4096
	ds_read_b128 v[232:235], v197 offset:5120
	ds_read_b128 v[236:239], v197 offset:6144
	ds_read_b128 v[240:243], v197 offset:7168
	global_load_lds_dwordx4 v[184:185], off
	v_lshl_add_u64 v[184:185], s[10:11], 0, v[156:157]
	s_add_i32 m0, s61, 0xe000
	s_nop 0
	global_load_lds_dwordx4 v[184:185], off
	s_waitcnt vmcnt(8)
	s_waitcnt lgkmcnt(0)
	s_barrier
	s_setprio 1
	s_waitcnt lgkmcnt(0)
	v_mfma_f32_16x16x32_bf16 v[134:137], v[18:21], v[198:201], v[134:137]
	v_mfma_f32_16x16x32_bf16 v[130:133], v[160:163], v[198:201], v[130:133]
	v_mfma_f32_16x16x32_bf16 v[118:121], v[18:21], v[206:209], v[118:121]
	v_mfma_f32_16x16x32_bf16 v[114:117], v[160:163], v[206:209], v[114:117]
	v_mfma_f32_16x16x32_bf16 v[102:105], v[18:21], v[214:217], v[102:105]
	v_mfma_f32_16x16x32_bf16 v[98:101], v[160:163], v[214:217], v[98:101]
	v_mfma_f32_16x16x32_bf16 v[86:89], v[18:21], v[236:239], v[86:89]
	v_mfma_f32_16x16x32_bf16 v[82:85], v[160:163], v[236:239], v[82:85]
	v_mfma_f32_16x16x32_bf16 v[134:137], v[22:25], v[202:205], v[134:137]
	v_mfma_f32_16x16x32_bf16 v[130:133], v[164:167], v[202:205], v[130:133]
	v_mfma_f32_16x16x32_bf16 v[118:121], v[22:25], v[210:213], v[118:121]
	v_mfma_f32_16x16x32_bf16 v[114:117], v[164:167], v[210:213], v[114:117]
	v_mfma_f32_16x16x32_bf16 v[102:105], v[22:25], v[232:235], v[102:105]
	v_mfma_f32_16x16x32_bf16 v[98:101], v[164:167], v[232:235], v[98:101]
	v_mfma_f32_16x16x32_bf16 v[86:89], v[22:25], v[240:243], v[86:89]
	v_mfma_f32_16x16x32_bf16 v[82:85], v[164:167], v[240:243], v[82:85]
	s_setprio 0
	s_setprio 1
	v_mfma_f32_16x16x32_bf16 v[126:129], v[168:171], v[198:201], v[126:129]
	v_mfma_f32_16x16x32_bf16 v[122:125], v[176:179], v[198:201], v[122:125]
	v_mfma_f32_16x16x32_bf16 v[110:113], v[168:171], v[206:209], v[110:113]
	v_mfma_f32_16x16x32_bf16 v[106:109], v[176:179], v[206:209], v[106:109]
	v_mfma_f32_16x16x32_bf16 v[94:97], v[168:171], v[214:217], v[94:97]
	v_mfma_f32_16x16x32_bf16 v[90:93], v[176:179], v[214:217], v[90:93]
	v_mfma_f32_16x16x32_bf16 v[78:81], v[168:171], v[236:239], v[78:81]
	v_mfma_f32_16x16x32_bf16 v[74:77], v[176:179], v[236:239], v[74:77]
	v_mfma_f32_16x16x32_bf16 v[126:129], v[172:175], v[202:205], v[126:129]
	v_mfma_f32_16x16x32_bf16 v[122:125], v[180:183], v[202:205], v[122:125]
	v_mfma_f32_16x16x32_bf16 v[110:113], v[172:175], v[210:213], v[110:113]
	v_mfma_f32_16x16x32_bf16 v[106:109], v[180:183], v[210:213], v[106:109]
	v_mfma_f32_16x16x32_bf16 v[94:97], v[172:175], v[232:235], v[94:97]
	v_mfma_f32_16x16x32_bf16 v[90:93], v[180:183], v[232:235], v[90:93]
	v_mfma_f32_16x16x32_bf16 v[78:81], v[172:175], v[240:243], v[78:81]
	s_barrier
	v_mfma_f32_16x16x32_bf16 v[74:77], v[180:183], v[240:243], v[74:77]
	s_setprio 0
	s_add_i32 s41, s41, s56
	v_lshl_add_u64 v[184:185], s[12:13], 0, v[142:143]
	s_mov_b32 m0, s41
	ds_read_b128 v[198:201], v197 offset:16384
	ds_read_b128 v[202:205], v197 offset:17408
	ds_read_b128 v[206:209], v197 offset:18432
	ds_read_b128 v[210:213], v197 offset:19456
	ds_read_b128 v[214:217], v197 offset:20480
	ds_read_b128 v[232:235], v197 offset:21504
	ds_read_b128 v[236:239], v197 offset:22528
	ds_read_b128 v[240:243], v197 offset:23552
	global_load_lds_dwordx4 v[184:185], off
	s_add_i32 m0, s41, 0x2000
	s_add_u32 s44, s12, 0x80000
	v_lshl_add_u64 v[190:191], s[12:13], 0, v[138:139]
	s_addc_u32 s45, s13, 0
	s_add_i32 s41, s43, s56
	global_load_lds_dwordx4 v[190:191], off
	v_lshl_add_u64 v[192:193], s[44:45], 0, v[142:143]
	s_mov_b32 m0, s41
	v_lshl_add_u64 v[194:195], s[14:15], 0, v[140:141]
	global_load_lds_dwordx4 v[192:193], off
	v_lshl_add_u64 v[192:193], s[44:45], 0, v[138:139]
	s_add_i32 m0, s41, 0x2000
	s_nop 0
	global_load_lds_dwordx4 v[192:193], off
	v_lshl_add_u64 v[192:193], s[14:15], 0, v[144:145]
	s_mov_b32 m0, s61
	s_nop 0
	global_load_lds_dwordx4 v[192:193], off
	s_mov_b32 m0, s62
	s_nop 0
	global_load_lds_dwordx4 v[194:195], off
	s_waitcnt vmcnt(8)
	s_waitcnt lgkmcnt(0)
	s_barrier
; #define PG8_STAGE(bufoff, gbase, voff) do { _Pragma("unroll") for (int _i = 0; _i < 2; ++_i) \
;         __builtin_amdgcn_global_load_lds((const unsigned*)((const char*)(gbase) + (voff)[_i]), (PG8_LAS unsigned*)(lds + (bufoff) + ldsw + _i * 8192), 16, 0, 0); } while (0)
; #define PG8_LDA(dst, b, h) do { _Pragma("unroll") for (int m = 0; m < 4; ++m) _Pragma("unroll") for (int k = 0; k < 2; ++k) dst[m][k] = *(const PG8_LAS bf16x8*)(lds + PG8_SA(b, h) + aoff + m * 2048 + k * 1024); } while (0)
; #define PG8_LDB(dst, b, h) do { _Pragma("unroll") for (int n = 0; n < 2; ++n) _Pragma("unroll") for (int k = 0; k < 2; ++k) dst[n][k] = *(const PG8_LAS bf16x8*)(lds + PG8_SB(b, h) + boff + n * 2048 + k * 1024); } while (0)
; #define PG8_MMA(ai, bj, At, Bt) do { __builtin_amdgcn_s_setprio(1); _Pragma("unroll") for (int m = 0; m < 4; ++m) _Pragma("unroll") for (int n = 0; n < 2; ++n) _Pragma("unroll") for (int k = 0; k < 2; ++k) \
;         acc[ai][bj][m][n] = __builtin_amdgcn_mfma_f32_16x16x32_bf16(Bt[n][k], At[m][k], acc[ai][bj][m][n], 0, 0, 0); __builtin_amdgcn_s_setprio(0); } while (0)
; #define PG8_WAIT_V(n) asm volatile("s_waitcnt vmcnt(" #n ")" ::: "memory")
; #define PG8_WAIT_L(n) asm volatile("s_waitcnt lgkmcnt(" #n ")" ::: "memory")
; #define PG8_BAR __builtin_amdgcn_s_barrier()
; #define PG8_SCHED __builtin_amdgcn_sched_barrier(0)
; template <class Epi, class Sched, bool ALIGN_EPI = false, bool SP2 = false>
; __device__ __forceinline__ void gemm_phase(PG8_LAS unsigned char* lds, const Gemm g, const Sched& S, const Epi& E) {
;     ...
;             PG8_WAIT_V(8); PG8_WAIT_L(0); PG8_BAR; PG8_MMA(1, 0, At, B0); PG8_MMA(1, 1, At, B1); PG8_BAR; PG8_SCHED;
;             PG8_LDB(B0, 1, 0); PG8_LDB(B1, 1, 1); PG8_SCHED; PG8_LDA(At, 1, 0); PG8_STAGE(PG8_SA(0, 1), a2 + hstep, voffA);
;             PG8_WAIT_V(8); PG8_WAIT_L(0); PG8_BAR; PG8_MMA(0, 0, At, B0); PG8_MMA(0, 1, At, B1); PG8_BAR; PG8_SCHED;
	s_setprio 1
	s_waitcnt lgkmcnt(0)
	v_mfma_f32_16x16x32_bf16 v[70:73], v[18:21], v[198:201], v[70:73]
	v_mfma_f32_16x16x32_bf16 v[66:69], v[160:163], v[198:201], v[66:69]
	v_mfma_f32_16x16x32_bf16 v[54:57], v[18:21], v[206:209], v[54:57]
	v_mfma_f32_16x16x32_bf16 v[50:53], v[160:163], v[206:209], v[50:53]
	v_mfma_f32_16x16x32_bf16 v[38:41], v[18:21], v[214:217], v[38:41]
	v_mfma_f32_16x16x32_bf16 v[34:37], v[160:163], v[214:217], v[34:37]
	v_mfma_f32_16x16x32_bf16 v[14:17], v[18:21], v[236:239], v[14:17]
	v_mfma_f32_16x16x32_bf16 v[10:13], v[160:163], v[236:239], v[10:13]
	v_mfma_f32_16x16x32_bf16 v[70:73], v[22:25], v[202:205], v[70:73]
	v_mfma_f32_16x16x32_bf16 v[66:69], v[164:167], v[202:205], v[66:69]
	v_mfma_f32_16x16x32_bf16 v[54:57], v[22:25], v[210:213], v[54:57]
	v_mfma_f32_16x16x32_bf16 v[50:53], v[164:167], v[210:213], v[50:53]
	v_mfma_f32_16x16x32_bf16 v[38:41], v[22:25], v[232:235], v[38:41]
	v_mfma_f32_16x16x32_bf16 v[34:37], v[164:167], v[232:235], v[34:37]
	v_mfma_f32_16x16x32_bf16 v[14:17], v[22:25], v[240:243], v[14:17]
	v_mfma_f32_16x16x32_bf16 v[10:13], v[164:167], v[240:243], v[10:13]
	s_setprio 0
	s_setprio 1
	v_mfma_f32_16x16x32_bf16 v[46:49], v[168:171], v[206:209], v[46:49]
	v_mfma_f32_16x16x32_bf16 v[42:45], v[176:179], v[206:209], v[42:45]
	v_mfma_f32_16x16x32_bf16 v[30:33], v[168:171], v[214:217], v[30:33]
	v_mfma_f32_16x16x32_bf16 v[26:29], v[176:179], v[214:217], v[26:29]
	v_mfma_f32_16x16x32_bf16 v[6:9], v[168:171], v[236:239], v[6:9]
	v_mfma_f32_16x16x32_bf16 v[2:5], v[176:179], v[236:239], v[2:5]
	v_mfma_f32_16x16x32_bf16 v[18:21], v[168:171], v[198:201], v[62:65]
	v_mfma_f32_16x16x32_bf16 v[22:25], v[176:179], v[198:201], v[58:61]
	v_mfma_f32_16x16x32_bf16 v[46:49], v[172:175], v[210:213], v[46:49]
	v_mfma_f32_16x16x32_bf16 v[42:45], v[180:183], v[210:213], v[42:45]
	v_mfma_f32_16x16x32_bf16 v[30:33], v[172:175], v[232:235], v[30:33]
	v_mfma_f32_16x16x32_bf16 v[26:29], v[180:183], v[232:235], v[26:29]
	v_mfma_f32_16x16x32_bf16 v[6:9], v[172:175], v[240:243], v[6:9]
	v_mfma_f32_16x16x32_bf16 v[2:5], v[180:183], v[240:243], v[2:5]
	v_mfma_f32_16x16x32_bf16 v[18:21], v[172:175], v[202:205], v[18:21]
	s_barrier
	v_mfma_f32_16x16x32_bf16 v[22:25], v[180:183], v[202:205], v[22:25]
	s_setprio 0
	s_add_i32 s41, 0, 0x18000
	v_add_u32_e32 v0, s41, v196
	s_add_i32 s43, 0, 0x1c000
	ds_read_b128 v[58:61], v0
	ds_read_b128 v[62:65], v0 offset:1024
	ds_read_b128 v[160:163], v0 offset:2048
	ds_read_b128 v[164:167], v0 offset:3072
	v_add_u32_e32 v0, s43, v196
	ds_read_b128 v[168:171], v0
	ds_read_b128 v[172:175], v0 offset:1024
	ds_read_b128 v[176:179], v0 offset:2048
	ds_read_b128 v[180:183], v0 offset:3072
	s_add_u32 s14, s14, 0x80000
	s_addc_u32 s15, s15, 0
	s_mov_b32 m0, s63
	v_lshl_add_u64 v[218:219], s[14:15], 0, v[144:145]
	ds_read_b128 v[198:201], v197 offset:32768
	ds_read_b128 v[202:205], v197 offset:33792
	ds_read_b128 v[206:209], v197 offset:34816
	ds_read_b128 v[210:213], v197 offset:35840
	ds_read_b128 v[214:217], v197 offset:36864
	ds_read_b128 v[232:235], v197 offset:37888
	ds_read_b128 v[236:239], v197 offset:38912
	ds_read_b128 v[240:243], v197 offset:39936
	global_load_lds_dwordx4 v[218:219], off
	v_lshl_add_u64 v[218:219], s[14:15], 0, v[140:141]
	s_mov_b32 m0, s64
	s_nop 0
	global_load_lds_dwordx4 v[218:219], off
	s_waitcnt vmcnt(8)
	s_waitcnt lgkmcnt(0)
	s_barrier
	s_setprio 1
	s_waitcnt lgkmcnt(0)
	v_mfma_f32_16x16x32_bf16 v[134:137], v[58:61], v[198:201], v[134:137]
	v_mfma_f32_16x16x32_bf16 v[130:133], v[160:163], v[198:201], v[130:133]
	v_mfma_f32_16x16x32_bf16 v[118:121], v[58:61], v[206:209], v[118:121]
	v_mfma_f32_16x16x32_bf16 v[114:117], v[160:163], v[206:209], v[114:117]
	v_mfma_f32_16x16x32_bf16 v[102:105], v[58:61], v[214:217], v[102:105]
	v_mfma_f32_16x16x32_bf16 v[98:101], v[160:163], v[214:217], v[98:101]
	v_mfma_f32_16x16x32_bf16 v[86:89], v[58:61], v[236:239], v[86:89]
	v_mfma_f32_16x16x32_bf16 v[82:85], v[160:163], v[236:239], v[82:85]
	v_mfma_f32_16x16x32_bf16 v[134:137], v[62:65], v[202:205], v[134:137]
	v_mfma_f32_16x16x32_bf16 v[130:133], v[164:167], v[202:205], v[130:133]
	v_mfma_f32_16x16x32_bf16 v[118:121], v[62:65], v[210:213], v[118:121]
	v_mfma_f32_16x16x32_bf16 v[114:117], v[164:167], v[210:213], v[114:117]
	v_mfma_f32_16x16x32_bf16 v[102:105], v[62:65], v[232:235], v[102:105]
	v_mfma_f32_16x16x32_bf16 v[98:101], v[164:167], v[232:235], v[98:101]
	v_mfma_f32_16x16x32_bf16 v[86:89], v[62:65], v[240:243], v[86:89]
	v_mfma_f32_16x16x32_bf16 v[82:85], v[164:167], v[240:243], v[82:85]
	s_setprio 0
	s_setprio 1
	v_mfma_f32_16x16x32_bf16 v[126:129], v[168:171], v[198:201], v[126:129]
	v_mfma_f32_16x16x32_bf16 v[122:125], v[176:179], v[198:201], v[122:125]
	v_mfma_f32_16x16x32_bf16 v[110:113], v[168:171], v[206:209], v[110:113]
	v_mfma_f32_16x16x32_bf16 v[106:109], v[176:179], v[206:209], v[106:109]
	v_mfma_f32_16x16x32_bf16 v[94:97], v[168:171], v[214:217], v[94:97]
	v_mfma_f32_16x16x32_bf16 v[90:93], v[176:179], v[214:217], v[90:93]
	v_mfma_f32_16x16x32_bf16 v[78:81], v[168:171], v[236:239], v[78:81]
	v_mfma_f32_16x16x32_bf16 v[74:77], v[176:179], v[236:239], v[74:77]
	v_mfma_f32_16x16x32_bf16 v[126:129], v[172:175], v[202:205], v[126:129]
	v_mfma_f32_16x16x32_bf16 v[122:125], v[180:183], v[202:205], v[122:125]
	v_mfma_f32_16x16x32_bf16 v[110:113], v[172:175], v[210:213], v[110:113]
	v_mfma_f32_16x16x32_bf16 v[106:109], v[180:183], v[210:213], v[106:109]
	v_mfma_f32_16x16x32_bf16 v[94:97], v[172:175], v[232:235], v[94:97]
	v_mfma_f32_16x16x32_bf16 v[90:93], v[180:183], v[232:235], v[90:93]
	v_mfma_f32_16x16x32_bf16 v[78:81], v[172:175], v[240:243], v[78:81]
	s_barrier
; #define PG8_STAGE(bufoff, gbase, voff) do { _Pragma("unroll") for (int _i = 0; _i < 2; ++_i) \
;         __builtin_amdgcn_global_load_lds((const unsigned*)((const char*)(gbase) + (voff)[_i]), (PG8_LAS unsigned*)(lds + (bufoff) + ldsw + _i * 8192), 16, 0, 0); } while (0)
; #define PG8_LDA(dst, b, h) do { _Pragma("unroll") for (int m = 0; m < 4; ++m) _Pragma("unroll") for (int k = 0; k < 2; ++k) dst[m][k] = *(const PG8_LAS bf16x8*)(lds + PG8_SA(b, h) + aoff + m * 2048 + k * 1024); } while (0)
; #define PG8_MMA(ai, bj, At, Bt) do { __builtin_amdgcn_s_setprio(1); _Pragma("unroll") for (int m = 0; m < 4; ++m) _Pragma("unroll") for (int n = 0; n < 2; ++n) _Pragma("unroll") for (int k = 0; k < 2; ++k) \
;         acc[ai][bj][m][n] = __builtin_amdgcn_mfma_f32_16x16x32_bf16(Bt[n][k], At[m][k], acc[ai][bj][m][n], 0, 0, 0); __builtin_amdgcn_s_setprio(0); } while (0)
; #define PG8_WAIT_V(n) asm volatile("s_waitcnt vmcnt(" #n ")" ::: "memory")
; #define PG8_WAIT_L(n) asm volatile("s_waitcnt lgkmcnt(" #n ")" ::: "memory")
; #define PG8_BAR __builtin_amdgcn_s_barrier()
; #define PG8_SCHED __builtin_amdgcn_sched_barrier(0)
; template <class Epi, class Sched, bool ALIGN_EPI = false, bool SP2 = false>
; __device__ __forceinline__ void gemm_phase(PG8_LAS unsigned char* lds, const Gemm g, const Sched& S, const Epi& E) {
;     ...
;         for (int t = 0; t < nt; t += 2) {
;             const bool last = (t == nt - 2);
;     ...
;             PG8_WAIT_V(8); PG8_WAIT_L(0); PG8_BAR; PG8_MMA(0, 0, At, B0); PG8_MMA(0, 1, At, B1); PG8_BAR; PG8_SCHED;
;             PG8_LDA(At, 1, 1); PG8_STAGE(PG8_SB(1, 0), b3, voffB); PG8_STAGE(PG8_SB(1, 1), b3 + hstep, voffB); PG8_STAGE(PG8_SA(1, 0), a3, voffA);
;             PG8_WAIT_V(8); PG8_WAIT_L(0); PG8_BAR; PG8_MMA(1, 0, At, B0); PG8_MMA(1, 1, At, B1); PG8_BAR; PG8_SCHED;
	v_mfma_f32_16x16x32_bf16 v[74:77], v[180:183], v[240:243], v[74:77]
	s_setprio 0
	s_add_i32 s14, s41, s56
	v_lshl_add_u64 v[184:185], v[184:185], 0, s[46:47]
	s_mov_b32 m0, s14
	ds_read_b128 v[198:201], v197 offset:49152
	ds_read_b128 v[202:205], v197 offset:50176
	ds_read_b128 v[206:209], v197 offset:51200
	ds_read_b128 v[210:213], v197 offset:52224
	ds_read_b128 v[214:217], v197 offset:53248
	ds_read_b128 v[232:235], v197 offset:54272
	ds_read_b128 v[236:239], v197 offset:55296
	ds_read_b128 v[240:243], v197 offset:56320
	global_load_lds_dwordx4 v[184:185], off
	s_add_i32 m0, s14, 0x2000
	s_add_u32 s12, s12, 0x80080
	v_lshl_add_u64 v[184:185], v[190:191], 0, s[46:47]
	s_addc_u32 s13, s13, 0
	s_add_i32 s14, s43, s56
	global_load_lds_dwordx4 v[184:185], off
	v_lshl_add_u64 v[184:185], s[12:13], 0, v[142:143]
	s_mov_b32 m0, s14
	s_nop 0
	global_load_lds_dwordx4 v[184:185], off
	v_lshl_add_u64 v[184:185], s[12:13], 0, v[138:139]
	s_add_i32 m0, s14, 0x2000
	s_nop 0
	global_load_lds_dwordx4 v[184:185], off
	v_lshl_add_u64 v[184:185], v[192:193], 0, s[46:47]
	s_mov_b32 m0, s69
	s_nop 0
	global_load_lds_dwordx4 v[184:185], off
	v_lshl_add_u64 v[184:185], v[194:195], 0, s[46:47]
	s_mov_b32 m0, s70
	s_nop 0
	global_load_lds_dwordx4 v[184:185], off
	s_waitcnt vmcnt(8)
	s_waitcnt lgkmcnt(0)
	s_barrier
	s_setprio 1
	s_waitcnt lgkmcnt(0)
	v_mfma_f32_16x16x32_bf16 v[70:73], v[58:61], v[198:201], v[70:73]
	v_mfma_f32_16x16x32_bf16 v[66:69], v[160:163], v[198:201], v[66:69]
	v_mfma_f32_16x16x32_bf16 v[54:57], v[58:61], v[206:209], v[54:57]
	v_mfma_f32_16x16x32_bf16 v[50:53], v[160:163], v[206:209], v[50:53]
	v_mfma_f32_16x16x32_bf16 v[38:41], v[58:61], v[214:217], v[38:41]
	v_mfma_f32_16x16x32_bf16 v[34:37], v[160:163], v[214:217], v[34:37]
	v_mfma_f32_16x16x32_bf16 v[14:17], v[58:61], v[236:239], v[14:17]
	v_mfma_f32_16x16x32_bf16 v[10:13], v[160:163], v[236:239], v[10:13]
	v_mfma_f32_16x16x32_bf16 v[70:73], v[62:65], v[202:205], v[70:73]
	v_mfma_f32_16x16x32_bf16 v[66:69], v[164:167], v[202:205], v[66:69]
	v_mfma_f32_16x16x32_bf16 v[54:57], v[62:65], v[210:213], v[54:57]
	v_mfma_f32_16x16x32_bf16 v[50:53], v[164:167], v[210:213], v[50:53]
	v_mfma_f32_16x16x32_bf16 v[38:41], v[62:65], v[232:235], v[38:41]
	v_mfma_f32_16x16x32_bf16 v[34:37], v[164:167], v[232:235], v[34:37]
	v_mfma_f32_16x16x32_bf16 v[14:17], v[62:65], v[240:243], v[14:17]
	v_mfma_f32_16x16x32_bf16 v[10:13], v[164:167], v[240:243], v[10:13]
	s_setprio 0
	s_setprio 1
	v_mfma_f32_16x16x32_bf16 v[18:21], v[168:171], v[198:201], v[18:21]
	v_mfma_f32_16x16x32_bf16 v[62:65], v[172:175], v[202:205], v[18:21]
	v_mfma_f32_16x16x32_bf16 v[18:21], v[176:179], v[198:201], v[22:25]
	v_mfma_f32_16x16x32_bf16 v[58:61], v[180:183], v[202:205], v[18:21]
	v_mfma_f32_16x16x32_bf16 v[18:21], v[168:171], v[206:209], v[46:49]
	v_mfma_f32_16x16x32_bf16 v[46:49], v[172:175], v[210:213], v[18:21]
	v_mfma_f32_16x16x32_bf16 v[18:21], v[176:179], v[206:209], v[42:45]
	v_mfma_f32_16x16x32_bf16 v[42:45], v[180:183], v[210:213], v[18:21]
	v_mfma_f32_16x16x32_bf16 v[18:21], v[168:171], v[214:217], v[30:33]
	v_mfma_f32_16x16x32_bf16 v[30:33], v[172:175], v[232:235], v[18:21]
	v_mfma_f32_16x16x32_bf16 v[18:21], v[176:179], v[214:217], v[26:29]
	v_mfma_f32_16x16x32_bf16 v[6:9], v[168:171], v[236:239], v[6:9]
	v_mfma_f32_16x16x32_bf16 v[2:5], v[176:179], v[236:239], v[2:5]
	v_mfma_f32_16x16x32_bf16 v[26:29], v[180:183], v[232:235], v[18:21]
	v_mfma_f32_16x16x32_bf16 v[6:9], v[172:175], v[240:243], v[6:9]
	s_barrier
	v_mfma_f32_16x16x32_bf16 v[2:5], v[180:183], v[240:243], v[2:5]
	s_setprio 0
	s_add_i32 s40, s40, 2
	s_add_u32 s38, s38, 0x100
	s_addc_u32 s39, s39, 0
	s_add_u32 s10, s10, 0x100
	s_addc_u32 s11, s11, 0
	s_cmp_gt_u32 s40, 29
	s_cbranch_scc0 .LBB0_213
	s_and_b64 vcc, exec, s[24:25]
	s_cbranch_vccz .LBB0_216
	s_barrier

; #define PG8_STAGE(bufoff, gbase, voff) do { _Pragma("unroll") for (int _i = 0; _i < 2; ++_i) \
;         __builtin_amdgcn_global_load_lds((const unsigned*)((const char*)(gbase) + (voff)[_i]), (PG8_LAS unsigned*)(lds + (bufoff) + ldsw + _i * 8192), 16, 0, 0); } while (0)
; #define PG8_LDA(dst, b, h) do { _Pragma("unroll") for (int m = 0; m < 4; ++m) _Pragma("unroll") for (int k = 0; k < 2; ++k) dst[m][k] = *(const PG8_LAS bf16x8*)(lds + PG8_SA(b, h) + aoff + m * 2048 + k * 1024); } while (0)
; #define PG8_LDB(dst, b, h) do { _Pragma("unroll") for (int n = 0; n < 2; ++n) _Pragma("unroll") for (int k = 0; k < 2; ++k) dst[n][k] = *(const PG8_LAS bf16x8*)(lds + PG8_SB(b, h) + boff + n * 2048 + k * 1024); } while (0)
; #define PG8_MMA(ai, bj, At, Bt) do { __builtin_amdgcn_s_setprio(1); _Pragma("unroll") for (int m = 0; m < 4; ++m) _Pragma("unroll") for (int n = 0; n < 2; ++n) _Pragma("unroll") for (int k = 0; k < 2; ++k) \
;         acc[ai][bj][m][n] = __builtin_amdgcn_mfma_f32_16x16x32_bf16(Bt[n][k], At[m][k], acc[ai][bj][m][n], 0, 0, 0); __builtin_amdgcn_s_setprio(0); } while (0)
; #define PG8_WAIT_V(n) asm volatile("s_waitcnt vmcnt(" #n ")" ::: "memory")
; #define PG8_BAR __builtin_amdgcn_s_barrier()
; template <class Epi, class Sched, bool ALIGN_EPI = false, bool SP2 = false>
; __device__ __forceinline__ void gemm_phase(PG8_LAS unsigned char* lds, const Gemm g, const Sched& S, const Epi& E) {
;     ...
;         for (int t = 0; t < nt; t += 2) {
;             const bool last = (t == nt - 2);
;             const char* a1 = cA + (size_t)(t + 1) * kstep;
;             const char* a2 = last ? nA : cA + (size_t)(t + 2) * kstep; const char* b2 = last ? nB : cB + (size_t)(t + 2) * kstep;
;             const char* a3 = a2 + kstep; const char* b3 = b2 + kstep;
;             if (last && has_next) S.a_ready(nxt);
;             if constexpr (SP2) {
;             PG8_LDB(B0, 0, 0); PG8_LDB(B1, 0, 1); PG8_SCHED; PG8_LDA(At, 0, 0); PG8_STAGE(PG8_SA(1, 1), a1 + hstep, voffA);
;             PG8_WAIT_V(8); PG8_WAIT_L(0); PG8_BAR; PG8_MMA(0, 0, At, B0); PG8_MMA(0, 1, At, B1); PG8_BAR; PG8_SCHED;
;             PG8_LDA(At, 0, 1); PG8_STAGE(PG8_SB(0, 0), b2, voffB); PG8_STAGE(PG8_SB(0, 1), b2 + hstep, voffB); PG8_STAGE(PG8_SA(0, 0), a2, voffA);
;             PG8_WAIT_V(8); PG8_WAIT_L(0); PG8_BAR; PG8_MMA(1, 0, At, B0); PG8_MMA(1, 1, At, B1); PG8_BAR; PG8_SCHED;
.LBB0_1113:
	s_add_u32 s24, s22, 0xfff80080
	s_addc_u32 s25, s23, -1
	s_add_i32 s48, 0, 0x10000
	s_cmp_eq_u32 s47, 28
	s_cselect_b32 s27, s13, s25
	s_cselect_b32 s26, s43, s24
	v_add_u32_e32 v0, s48, v178
	s_cselect_b32 s25, s15, s46
	s_cselect_b32 s24, s44, s45
	s_add_i32 s50, 0, 0x14000
	ds_read_b128 v[130:133], v0
	ds_read_b128 v[134:137], v0 offset:1024
	ds_read_b128 v[138:141], v0 offset:2048
	ds_read_b128 v[154:157], v0 offset:3072
	v_add_u32_e32 v0, s50, v178
	ds_read_b128 v[158:161], v0
	ds_read_b128 v[162:165], v0 offset:1024
	ds_read_b128 v[166:169], v0 offset:2048
	ds_read_b128 v[170:173], v0 offset:3072
	v_lshl_add_u64 v[184:185], s[22:23], 0, v[152:153]
	s_add_i32 m0, s34, 0xc000
	ds_read_b128 v[174:177], v182
	ds_read_b128 v[190:193], v182 offset:1024
	ds_read_b128 v[194:197], v182 offset:2048
	ds_read_b128 v[198:201], v182 offset:3072
	ds_read_b128 v[202:205], v182 offset:4096
	ds_read_b128 v[206:209], v182 offset:5120
	ds_read_b128 v[210:213], v182 offset:6144
	ds_read_b128 v[214:217], v182 offset:7168
	global_load_lds_dwordx4 v[184:185], off
	v_lshl_add_u64 v[184:185], s[22:23], 0, v[150:151]
	s_add_i32 m0, s34, 0xe000
	s_nop 0
	global_load_lds_dwordx4 v[184:185], off
	s_waitcnt vmcnt(8)
	s_waitcnt lgkmcnt(0)
	s_barrier
	s_setprio 1
	s_waitcnt lgkmcnt(0)
	v_mfma_f32_16x16x32_bf16 v[126:129], v[130:133], v[174:177], v[126:129]
	v_mfma_f32_16x16x32_bf16 v[122:125], v[138:141], v[174:177], v[122:125]
	v_mfma_f32_16x16x32_bf16 v[110:113], v[130:133], v[194:197], v[110:113]
	v_mfma_f32_16x16x32_bf16 v[106:109], v[138:141], v[194:197], v[106:109]
	v_mfma_f32_16x16x32_bf16 v[94:97], v[130:133], v[202:205], v[94:97]
	v_mfma_f32_16x16x32_bf16 v[90:93], v[138:141], v[202:205], v[90:93]
	v_mfma_f32_16x16x32_bf16 v[78:81], v[130:133], v[210:213], v[78:81]
	v_mfma_f32_16x16x32_bf16 v[74:77], v[138:141], v[210:213], v[74:77]
	v_mfma_f32_16x16x32_bf16 v[126:129], v[134:137], v[190:193], v[126:129]
	v_mfma_f32_16x16x32_bf16 v[122:125], v[154:157], v[190:193], v[122:125]
	v_mfma_f32_16x16x32_bf16 v[110:113], v[134:137], v[198:201], v[110:113]
	v_mfma_f32_16x16x32_bf16 v[106:109], v[154:157], v[198:201], v[106:109]
	v_mfma_f32_16x16x32_bf16 v[94:97], v[134:137], v[206:209], v[94:97]
	v_mfma_f32_16x16x32_bf16 v[90:93], v[154:157], v[206:209], v[90:93]
	v_mfma_f32_16x16x32_bf16 v[78:81], v[134:137], v[214:217], v[78:81]
	v_mfma_f32_16x16x32_bf16 v[74:77], v[154:157], v[214:217], v[74:77]
	s_setprio 0
	s_setprio 1
	v_mfma_f32_16x16x32_bf16 v[118:121], v[158:161], v[174:177], v[118:121]
	v_mfma_f32_16x16x32_bf16 v[114:117], v[166:169], v[174:177], v[114:117]
	v_mfma_f32_16x16x32_bf16 v[102:105], v[158:161], v[194:197], v[102:105]
	v_mfma_f32_16x16x32_bf16 v[98:101], v[166:169], v[194:197], v[98:101]
	v_mfma_f32_16x16x32_bf16 v[86:89], v[158:161], v[202:205], v[86:89]
	v_mfma_f32_16x16x32_bf16 v[82:85], v[166:169], v[202:205], v[82:85]
	v_mfma_f32_16x16x32_bf16 v[70:73], v[158:161], v[210:213], v[70:73]
	v_mfma_f32_16x16x32_bf16 v[66:69], v[166:169], v[210:213], v[66:69]
	v_mfma_f32_16x16x32_bf16 v[118:121], v[162:165], v[190:193], v[118:121]
	v_mfma_f32_16x16x32_bf16 v[114:117], v[170:173], v[190:193], v[114:117]
	v_mfma_f32_16x16x32_bf16 v[102:105], v[162:165], v[198:201], v[102:105]
	v_mfma_f32_16x16x32_bf16 v[98:101], v[170:173], v[198:201], v[98:101]
	v_mfma_f32_16x16x32_bf16 v[86:89], v[162:165], v[206:209], v[86:89]
	v_mfma_f32_16x16x32_bf16 v[82:85], v[170:173], v[206:209], v[82:85]
	v_mfma_f32_16x16x32_bf16 v[70:73], v[162:165], v[214:217], v[70:73]
	s_barrier
	v_mfma_f32_16x16x32_bf16 v[66:69], v[170:173], v[214:217], v[66:69]
	s_setprio 0
	s_add_i32 s48, s48, s33
	v_lshl_add_u64 v[184:185], s[24:25], 0, v[146:147]
	s_mov_b32 m0, s48
	ds_read_b128 v[174:177], v182 offset:16384
	ds_read_b128 v[190:193], v182 offset:17408
	ds_read_b128 v[194:197], v182 offset:18432
	ds_read_b128 v[198:201], v182 offset:19456
	ds_read_b128 v[202:205], v182 offset:20480
	ds_read_b128 v[206:209], v182 offset:21504
	ds_read_b128 v[210:213], v182 offset:22528
	ds_read_b128 v[214:217], v182 offset:23552
	global_load_lds_dwordx4 v[184:185], off
	s_add_i32 m0, s48, 0x2000
	s_add_u32 s48, s24, 0x80000
	v_lshl_add_u64 v[218:219], s[24:25], 0, v[142:143]
	s_addc_u32 s49, s25, 0
	s_add_i32 s50, s50, s33
	global_load_lds_dwordx4 v[218:219], off
	v_lshl_add_u64 v[232:233], s[48:49], 0, v[146:147]
	s_mov_b32 m0, s50
	v_lshl_add_u64 v[234:235], s[26:27], 0, v[144:145]
	global_load_lds_dwordx4 v[232:233], off
	v_lshl_add_u64 v[232:233], s[48:49], 0, v[142:143]
	s_add_i32 m0, s50, 0x2000
	s_nop 0
	global_load_lds_dwordx4 v[232:233], off
	v_lshl_add_u64 v[232:233], s[26:27], 0, v[148:149]
	s_mov_b32 m0, s34
	s_nop 0
	global_load_lds_dwordx4 v[232:233], off
	s_mov_b32 m0, s35
	s_nop 0
	global_load_lds_dwordx4 v[234:235], off
	s_waitcnt vmcnt(8)
	s_waitcnt lgkmcnt(0)
	s_barrier
; #define PG8_STAGE(bufoff, gbase, voff) do { _Pragma("unroll") for (int _i = 0; _i < 2; ++_i) \
;         __builtin_amdgcn_global_load_lds((const unsigned*)((const char*)(gbase) + (voff)[_i]), (PG8_LAS unsigned*)(lds + (bufoff) + ldsw + _i * 8192), 16, 0, 0); } while (0)
; #define PG8_LDA(dst, b, h) do { _Pragma("unroll") for (int m = 0; m < 4; ++m) _Pragma("unroll") for (int k = 0; k < 2; ++k) dst[m][k] = *(const PG8_LAS bf16x8*)(lds + PG8_SA(b, h) + aoff + m * 2048 + k * 1024); } while (0)
; #define PG8_LDB(dst, b, h) do { _Pragma("unroll") for (int n = 0; n < 2; ++n) _Pragma("unroll") for (int k = 0; k < 2; ++k) dst[n][k] = *(const PG8_LAS bf16x8*)(lds + PG8_SB(b, h) + boff + n * 2048 + k * 1024); } while (0)
; #define PG8_MMA(ai, bj, At, Bt) do { __builtin_amdgcn_s_setprio(1); _Pragma("unroll") for (int m = 0; m < 4; ++m) _Pragma("unroll") for (int n = 0; n < 2; ++n) _Pragma("unroll") for (int k = 0; k < 2; ++k) \
;         acc[ai][bj][m][n] = __builtin_amdgcn_mfma_f32_16x16x32_bf16(Bt[n][k], At[m][k], acc[ai][bj][m][n], 0, 0, 0); __builtin_amdgcn_s_setprio(0); } while (0)
; #define PG8_WAIT_V(n) asm volatile("s_waitcnt vmcnt(" #n ")" ::: "memory")
; #define PG8_WAIT_L(n) asm volatile("s_waitcnt lgkmcnt(" #n ")" ::: "memory")
; #define PG8_BAR __builtin_amdgcn_s_barrier()
; #define PG8_SCHED __builtin_amdgcn_sched_barrier(0)
; template <class Epi, class Sched, bool ALIGN_EPI = false, bool SP2 = false>
; __device__ __forceinline__ void gemm_phase(PG8_LAS unsigned char* lds, const Gemm g, const Sched& S, const Epi& E) {
;     ...
;             PG8_WAIT_V(8); PG8_WAIT_L(0); PG8_BAR; PG8_MMA(1, 0, At, B0); PG8_MMA(1, 1, At, B1); PG8_BAR; PG8_SCHED;
;             PG8_LDB(B0, 1, 0); PG8_LDB(B1, 1, 1); PG8_SCHED; PG8_LDA(At, 1, 0); PG8_STAGE(PG8_SA(0, 1), a2 + hstep, voffA);
;             PG8_WAIT_V(8); PG8_WAIT_L(0); PG8_BAR; PG8_MMA(0, 0, At, B0); PG8_MMA(0, 1, At, B1); PG8_BAR; PG8_SCHED;
	s_setprio 1
	s_waitcnt lgkmcnt(0)
	v_mfma_f32_16x16x32_bf16 v[62:65], v[130:133], v[174:177], v[62:65]
	v_mfma_f32_16x16x32_bf16 v[58:61], v[138:141], v[174:177], v[58:61]
	v_mfma_f32_16x16x32_bf16 v[46:49], v[130:133], v[194:197], v[46:49]
	v_mfma_f32_16x16x32_bf16 v[42:45], v[138:141], v[194:197], v[42:45]
	v_mfma_f32_16x16x32_bf16 v[30:33], v[130:133], v[202:205], v[30:33]
	v_mfma_f32_16x16x32_bf16 v[26:29], v[138:141], v[202:205], v[26:29]
	v_mfma_f32_16x16x32_bf16 v[14:17], v[130:133], v[210:213], v[14:17]
	v_mfma_f32_16x16x32_bf16 v[10:13], v[138:141], v[210:213], v[10:13]
	v_mfma_f32_16x16x32_bf16 v[62:65], v[134:137], v[190:193], v[62:65]
	v_mfma_f32_16x16x32_bf16 v[58:61], v[154:157], v[190:193], v[58:61]
	v_mfma_f32_16x16x32_bf16 v[46:49], v[134:137], v[198:201], v[46:49]
	v_mfma_f32_16x16x32_bf16 v[42:45], v[154:157], v[198:201], v[42:45]
	v_mfma_f32_16x16x32_bf16 v[30:33], v[134:137], v[206:209], v[30:33]
	v_mfma_f32_16x16x32_bf16 v[26:29], v[154:157], v[206:209], v[26:29]
	v_mfma_f32_16x16x32_bf16 v[14:17], v[134:137], v[214:217], v[14:17]
	v_mfma_f32_16x16x32_bf16 v[10:13], v[154:157], v[214:217], v[10:13]
	s_setprio 0
	s_setprio 1
	v_mfma_f32_16x16x32_bf16 v[54:57], v[158:161], v[174:177], v[54:57]
	v_mfma_f32_16x16x32_bf16 v[50:53], v[166:169], v[174:177], v[50:53]
	v_mfma_f32_16x16x32_bf16 v[38:41], v[158:161], v[194:197], v[38:41]
	v_mfma_f32_16x16x32_bf16 v[34:37], v[166:169], v[194:197], v[34:37]
	v_mfma_f32_16x16x32_bf16 v[22:25], v[158:161], v[202:205], v[22:25]
	v_mfma_f32_16x16x32_bf16 v[18:21], v[166:169], v[202:205], v[18:21]
	v_mfma_f32_16x16x32_bf16 v[6:9], v[158:161], v[210:213], v[6:9]
	v_mfma_f32_16x16x32_bf16 v[2:5], v[166:169], v[210:213], v[2:5]
	v_mfma_f32_16x16x32_bf16 v[54:57], v[162:165], v[190:193], v[54:57]
	v_mfma_f32_16x16x32_bf16 v[50:53], v[170:173], v[190:193], v[50:53]
	v_mfma_f32_16x16x32_bf16 v[38:41], v[162:165], v[198:201], v[38:41]
	v_mfma_f32_16x16x32_bf16 v[34:37], v[170:173], v[198:201], v[34:37]
	v_mfma_f32_16x16x32_bf16 v[22:25], v[162:165], v[206:209], v[22:25]
	v_mfma_f32_16x16x32_bf16 v[18:21], v[170:173], v[206:209], v[18:21]
	v_mfma_f32_16x16x32_bf16 v[6:9], v[162:165], v[214:217], v[6:9]
	s_barrier
	v_mfma_f32_16x16x32_bf16 v[2:5], v[170:173], v[214:217], v[2:5]
	s_setprio 0
	s_add_i32 s48, 0, 0x18000
	v_add_u32_e32 v0, s48, v178
	s_add_i32 s49, 0, 0x1c000
	ds_read_b128 v[130:133], v0
	ds_read_b128 v[134:137], v0 offset:1024
	ds_read_b128 v[138:141], v0 offset:2048
	ds_read_b128 v[154:157], v0 offset:3072
	v_add_u32_e32 v0, s49, v178
	ds_read_b128 v[158:161], v0
	ds_read_b128 v[162:165], v0 offset:1024
	ds_read_b128 v[166:169], v0 offset:2048
	ds_read_b128 v[170:173], v0 offset:3072
	s_add_u32 s26, s26, 0x80000
	s_addc_u32 s27, s27, 0
	s_mov_b32 m0, s36
	v_lshl_add_u64 v[236:237], s[26:27], 0, v[148:149]
	ds_read_b128 v[174:177], v182 offset:32768
	ds_read_b128 v[190:193], v182 offset:33792
	ds_read_b128 v[194:197], v182 offset:34816
	ds_read_b128 v[198:201], v182 offset:35840
	ds_read_b128 v[202:205], v182 offset:36864
	ds_read_b128 v[206:209], v182 offset:37888
	ds_read_b128 v[210:213], v182 offset:38912
	ds_read_b128 v[214:217], v182 offset:39936
	global_load_lds_dwordx4 v[236:237], off
	v_lshl_add_u64 v[236:237], s[26:27], 0, v[144:145]
	s_mov_b32 m0, s37
	s_nop 0
	global_load_lds_dwordx4 v[236:237], off
	s_waitcnt vmcnt(8)
	s_waitcnt lgkmcnt(0)
	s_barrier
	s_setprio 1
	s_waitcnt lgkmcnt(0)
	v_mfma_f32_16x16x32_bf16 v[126:129], v[130:133], v[174:177], v[126:129]
	v_mfma_f32_16x16x32_bf16 v[122:125], v[138:141], v[174:177], v[122:125]
	v_mfma_f32_16x16x32_bf16 v[110:113], v[130:133], v[194:197], v[110:113]
	v_mfma_f32_16x16x32_bf16 v[106:109], v[138:141], v[194:197], v[106:109]
	v_mfma_f32_16x16x32_bf16 v[94:97], v[130:133], v[202:205], v[94:97]
	v_mfma_f32_16x16x32_bf16 v[90:93], v[138:141], v[202:205], v[90:93]
	v_mfma_f32_16x16x32_bf16 v[78:81], v[130:133], v[210:213], v[78:81]
	v_mfma_f32_16x16x32_bf16 v[74:77], v[138:141], v[210:213], v[74:77]
	v_mfma_f32_16x16x32_bf16 v[126:129], v[134:137], v[190:193], v[126:129]
	v_mfma_f32_16x16x32_bf16 v[122:125], v[154:157], v[190:193], v[122:125]
	v_mfma_f32_16x16x32_bf16 v[110:113], v[134:137], v[198:201], v[110:113]
	v_mfma_f32_16x16x32_bf16 v[106:109], v[154:157], v[198:201], v[106:109]
	v_mfma_f32_16x16x32_bf16 v[94:97], v[134:137], v[206:209], v[94:97]
	v_mfma_f32_16x16x32_bf16 v[90:93], v[154:157], v[206:209], v[90:93]
	v_mfma_f32_16x16x32_bf16 v[78:81], v[134:137], v[214:217], v[78:81]
	v_mfma_f32_16x16x32_bf16 v[74:77], v[154:157], v[214:217], v[74:77]
	s_setprio 0
	s_setprio 1
	v_mfma_f32_16x16x32_bf16 v[118:121], v[158:161], v[174:177], v[118:121]
	v_mfma_f32_16x16x32_bf16 v[114:117], v[166:169], v[174:177], v[114:117]
	v_mfma_f32_16x16x32_bf16 v[102:105], v[158:161], v[194:197], v[102:105]
	v_mfma_f32_16x16x32_bf16 v[98:101], v[166:169], v[194:197], v[98:101]
	v_mfma_f32_16x16x32_bf16 v[86:89], v[158:161], v[202:205], v[86:89]
	v_mfma_f32_16x16x32_bf16 v[82:85], v[166:169], v[202:205], v[82:85]
	v_mfma_f32_16x16x32_bf16 v[70:73], v[158:161], v[210:213], v[70:73]
	v_mfma_f32_16x16x32_bf16 v[66:69], v[166:169], v[210:213], v[66:69]
	v_mfma_f32_16x16x32_bf16 v[118:121], v[162:165], v[190:193], v[118:121]
	v_mfma_f32_16x16x32_bf16 v[114:117], v[170:173], v[190:193], v[114:117]
	v_mfma_f32_16x16x32_bf16 v[102:105], v[162:165], v[198:201], v[102:105]
	v_mfma_f32_16x16x32_bf16 v[98:101], v[170:173], v[198:201], v[98:101]
	v_mfma_f32_16x16x32_bf16 v[86:89], v[162:165], v[206:209], v[86:89]
	v_mfma_f32_16x16x32_bf16 v[82:85], v[170:173], v[206:209], v[82:85]
	v_mfma_f32_16x16x32_bf16 v[70:73], v[162:165], v[214:217], v[70:73]
	s_barrier
; #define PG8_STAGE(bufoff, gbase, voff) do { _Pragma("unroll") for (int _i = 0; _i < 2; ++_i) \
;         __builtin_amdgcn_global_load_lds((const unsigned*)((const char*)(gbase) + (voff)[_i]), (PG8_LAS unsigned*)(lds + (bufoff) + ldsw + _i * 8192), 16, 0, 0); } while (0)
; #define PG8_LDA(dst, b, h) do { _Pragma("unroll") for (int m = 0; m < 4; ++m) _Pragma("unroll") for (int k = 0; k < 2; ++k) dst[m][k] = *(const PG8_LAS bf16x8*)(lds + PG8_SA(b, h) + aoff + m * 2048 + k * 1024); } while (0)
; #define PG8_MMA(ai, bj, At, Bt) do { __builtin_amdgcn_s_setprio(1); _Pragma("unroll") for (int m = 0; m < 4; ++m) _Pragma("unroll") for (int n = 0; n < 2; ++n) _Pragma("unroll") for (int k = 0; k < 2; ++k) \
;         acc[ai][bj][m][n] = __builtin_amdgcn_mfma_f32_16x16x32_bf16(Bt[n][k], At[m][k], acc[ai][bj][m][n], 0, 0, 0); __builtin_amdgcn_s_setprio(0); } while (0)
; #define PG8_WAIT_V(n) asm volatile("s_waitcnt vmcnt(" #n ")" ::: "memory")
; #define PG8_WAIT_L(n) asm volatile("s_waitcnt lgkmcnt(" #n ")" ::: "memory")
; #define PG8_BAR __builtin_amdgcn_s_barrier()
; #define PG8_SCHED __builtin_amdgcn_sched_barrier(0)
; template <class Epi, class Sched, bool ALIGN_EPI = false, bool SP2 = false>
; __device__ __forceinline__ void gemm_phase(PG8_LAS unsigned char* lds, const Gemm g, const Sched& S, const Epi& E) {
;     ...
;         for (int t = 0; t < nt; t += 2) {
;             const bool last = (t == nt - 2);
;     ...
;             PG8_WAIT_V(8); PG8_WAIT_L(0); PG8_BAR; PG8_MMA(0, 0, At, B0); PG8_MMA(0, 1, At, B1); PG8_BAR; PG8_SCHED;
;             PG8_LDA(At, 1, 1); PG8_STAGE(PG8_SB(1, 0), b3, voffB); PG8_STAGE(PG8_SB(1, 1), b3 + hstep, voffB); PG8_STAGE(PG8_SA(1, 0), a3, voffA);
;             PG8_WAIT_V(8); PG8_WAIT_L(0); PG8_BAR; PG8_MMA(1, 0, At, B0); PG8_MMA(1, 1, At, B1); PG8_BAR; PG8_SCHED;
	v_mfma_f32_16x16x32_bf16 v[66:69], v[170:173], v[214:217], v[66:69]
	s_setprio 0
	s_add_i32 s26, s48, s33
	v_lshl_add_u64 v[184:185], v[184:185], 0, s[52:53]
	s_mov_b32 m0, s26
	ds_read_b128 v[174:177], v182 offset:49152
	ds_read_b128 v[190:193], v182 offset:50176
	ds_read_b128 v[194:197], v182 offset:51200
	ds_read_b128 v[198:201], v182 offset:52224
	ds_read_b128 v[202:205], v182 offset:53248
	ds_read_b128 v[206:209], v182 offset:54272
	ds_read_b128 v[210:213], v182 offset:55296
	ds_read_b128 v[214:217], v182 offset:56320
	global_load_lds_dwordx4 v[184:185], off
	s_add_i32 m0, s26, 0x2000
	s_add_u32 s24, s24, 0x80080
	v_lshl_add_u64 v[184:185], v[218:219], 0, s[52:53]
	s_addc_u32 s25, s25, 0
	s_add_i32 s26, s49, s33
	global_load_lds_dwordx4 v[184:185], off
	v_lshl_add_u64 v[184:185], s[24:25], 0, v[146:147]
	s_mov_b32 m0, s26
	s_nop 0
	global_load_lds_dwordx4 v[184:185], off
	v_lshl_add_u64 v[184:185], s[24:25], 0, v[142:143]
	s_add_i32 m0, s26, 0x2000
	s_nop 0
	global_load_lds_dwordx4 v[184:185], off
	v_lshl_add_u64 v[184:185], v[232:233], 0, s[52:53]
	s_mov_b32 m0, s38
	s_nop 0
	global_load_lds_dwordx4 v[184:185], off
	v_lshl_add_u64 v[184:185], v[234:235], 0, s[52:53]
	s_mov_b32 m0, s39
	s_nop 0
	global_load_lds_dwordx4 v[184:185], off
	s_waitcnt vmcnt(8)
	s_waitcnt lgkmcnt(0)
	s_barrier
	s_setprio 1
	s_waitcnt lgkmcnt(0)
	v_mfma_f32_16x16x32_bf16 v[62:65], v[130:133], v[174:177], v[62:65]
	v_mfma_f32_16x16x32_bf16 v[58:61], v[138:141], v[174:177], v[58:61]
	v_mfma_f32_16x16x32_bf16 v[46:49], v[130:133], v[194:197], v[46:49]
	v_mfma_f32_16x16x32_bf16 v[42:45], v[138:141], v[194:197], v[42:45]
	v_mfma_f32_16x16x32_bf16 v[30:33], v[130:133], v[202:205], v[30:33]
	v_mfma_f32_16x16x32_bf16 v[26:29], v[138:141], v[202:205], v[26:29]
	v_mfma_f32_16x16x32_bf16 v[14:17], v[130:133], v[210:213], v[14:17]
	v_mfma_f32_16x16x32_bf16 v[10:13], v[138:141], v[210:213], v[10:13]
	v_mfma_f32_16x16x32_bf16 v[62:65], v[134:137], v[190:193], v[62:65]
	v_mfma_f32_16x16x32_bf16 v[58:61], v[154:157], v[190:193], v[58:61]
	v_mfma_f32_16x16x32_bf16 v[46:49], v[134:137], v[198:201], v[46:49]
	v_mfma_f32_16x16x32_bf16 v[42:45], v[154:157], v[198:201], v[42:45]
	v_mfma_f32_16x16x32_bf16 v[30:33], v[134:137], v[206:209], v[30:33]
	v_mfma_f32_16x16x32_bf16 v[26:29], v[154:157], v[206:209], v[26:29]
	v_mfma_f32_16x16x32_bf16 v[14:17], v[134:137], v[214:217], v[14:17]
	v_mfma_f32_16x16x32_bf16 v[10:13], v[154:157], v[214:217], v[10:13]
	s_setprio 0
	s_setprio 1
	v_mfma_f32_16x16x32_bf16 v[54:57], v[158:161], v[174:177], v[54:57]
	v_mfma_f32_16x16x32_bf16 v[50:53], v[166:169], v[174:177], v[50:53]
	v_mfma_f32_16x16x32_bf16 v[38:41], v[158:161], v[194:197], v[38:41]
	v_mfma_f32_16x16x32_bf16 v[34:37], v[166:169], v[194:197], v[34:37]
	v_mfma_f32_16x16x32_bf16 v[22:25], v[158:161], v[202:205], v[22:25]
	v_mfma_f32_16x16x32_bf16 v[18:21], v[166:169], v[202:205], v[18:21]
	v_mfma_f32_16x16x32_bf16 v[6:9], v[158:161], v[210:213], v[6:9]
	v_mfma_f32_16x16x32_bf16 v[2:5], v[166:169], v[210:213], v[2:5]
	v_mfma_f32_16x16x32_bf16 v[54:57], v[162:165], v[190:193], v[54:57]
	v_mfma_f32_16x16x32_bf16 v[50:53], v[170:173], v[190:193], v[50:53]
	v_mfma_f32_16x16x32_bf16 v[38:41], v[162:165], v[198:201], v[38:41]
	v_mfma_f32_16x16x32_bf16 v[34:37], v[170:173], v[198:201], v[34:37]
	v_mfma_f32_16x16x32_bf16 v[22:25], v[162:165], v[206:209], v[22:25]
	v_mfma_f32_16x16x32_bf16 v[18:21], v[170:173], v[206:209], v[18:21]
	v_mfma_f32_16x16x32_bf16 v[6:9], v[162:165], v[214:217], v[6:9]
	s_barrier
	v_mfma_f32_16x16x32_bf16 v[2:5], v[170:173], v[214:217], v[2:5]
	s_setprio 0
	s_add_i32 s47, s47, 2
	s_add_u32 s45, s45, 0x100
	s_addc_u32 s46, s46, 0
	s_add_u32 s22, s22, 0x100
	s_addc_u32 s23, s23, 0
	s_cmp_gt_u32 s47, 29
	s_cbranch_scc0 .LBB0_1113
	s_and_b64 vcc, exec, s[10:11]
	s_cbranch_vccz .LBB0_1116
	s_barrier

; #define PG8_STAGE(bufoff, gbase, voff) do { _Pragma("unroll") for (int _i = 0; _i < 2; ++_i) \
;         __builtin_amdgcn_global_load_lds((const unsigned*)((const char*)(gbase) + (voff)[_i]), (PG8_LAS unsigned*)(lds + (bufoff) + ldsw + _i * 8192), 16, 0, 0); } while (0)
; #define PG8_LDA(dst, b, h) do { _Pragma("unroll") for (int m = 0; m < 4; ++m) _Pragma("unroll") for (int k = 0; k < 2; ++k) dst[m][k] = *(const PG8_LAS bf16x8*)(lds + PG8_SA(b, h) + aoff + m * 2048 + k * 1024); } while (0)
; #define PG8_LDB(dst, b, h) do { _Pragma("unroll") for (int n = 0; n < 2; ++n) _Pragma("unroll") for (int k = 0; k < 2; ++k) dst[n][k] = *(const PG8_LAS bf16x8*)(lds + PG8_SB(b, h) + boff + n * 2048 + k * 1024); } while (0)
; #define PG8_MMA(ai, bj, At, Bt) do { __builtin_amdgcn_s_setprio(1); _Pragma("unroll") for (int m = 0; m < 4; ++m) _Pragma("unroll") for (int n = 0; n < 2; ++n) _Pragma("unroll") for (int k = 0; k < 2; ++k) \
;         acc[ai][bj][m][n] = __builtin_amdgcn_mfma_f32_16x16x32_bf16(Bt[n][k], At[m][k], acc[ai][bj][m][n], 0, 0, 0); __builtin_amdgcn_s_setprio(0); } while (0)
; #define PG8_WAIT_V(n) asm volatile("s_waitcnt vmcnt(" #n ")" ::: "memory")
; #define PG8_BAR __builtin_amdgcn_s_barrier()
; template <class Epi, class Sched, bool ALIGN_EPI = false, bool SP2 = false>
; __device__ __forceinline__ void gemm_phase(PG8_LAS unsigned char* lds, const Gemm g, const Sched& S, const Epi& E) {
;     ...
;         for (int t = 0; t < nt; t += 2) {
;             const bool last = (t == nt - 2);
;             const char* a1 = cA + (size_t)(t + 1) * kstep;
;             const char* a2 = last ? nA : cA + (size_t)(t + 2) * kstep; const char* b2 = last ? nB : cB + (size_t)(t + 2) * kstep;
;             const char* a3 = a2 + kstep; const char* b3 = b2 + kstep;
;             if (last && has_next) S.a_ready(nxt);
;             if constexpr (SP2) {
;             PG8_LDB(B0, 0, 0); PG8_LDB(B1, 0, 1); PG8_SCHED; PG8_LDA(At, 0, 0); PG8_STAGE(PG8_SA(1, 1), a1 + hstep, voffA);
;             PG8_WAIT_V(8); PG8_WAIT_L(0); PG8_BAR; PG8_MMA(0, 0, At, B0); PG8_MMA(0, 1, At, B1); PG8_BAR; PG8_SCHED;
;             PG8_LDA(At, 0, 1); PG8_STAGE(PG8_SB(0, 0), b2, voffB); PG8_STAGE(PG8_SB(0, 1), b2 + hstep, voffB); PG8_STAGE(PG8_SA(0, 0), a2, voffA);
;             PG8_WAIT_V(8); PG8_WAIT_L(0); PG8_BAR; PG8_MMA(1, 0, At, B0); PG8_MMA(1, 1, At, B1); PG8_BAR; PG8_SCHED;
.LBB0_1182:
	s_add_u32 s26, s4, 0xfff80080
	s_addc_u32 s27, s5, -1
	s_add_i32 s51, 0, 0x10000
	s_cmp_eq_u32 s50, 28
	s_cselect_b32 s29, s21, s27
	s_cselect_b32 s28, s46, s26
	s_cselect_b32 s27, s19, s49
	s_cselect_b32 s26, s47, s48
	s_add_i32 s54, 0, 0x14000
	v_add_u32_e32 v142, s51, v232
	v_add_u32_e32 v158, s54, v232
	ds_read_b128 v[122:125], v142
	ds_read_b128 v[126:129], v142 offset:1024
	ds_read_b128 v[138:141], v142 offset:2048
	ds_read_b128 v[142:145], v142 offset:3072
	ds_read_b128 v[146:149], v158
	ds_read_b128 v[150:153], v158 offset:1024
	ds_read_b128 v[154:157], v158 offset:2048
	ds_read_b128 v[158:161], v158 offset:3072
	v_lshl_add_u64 v[208:209], s[4:5], 0, v[202:203]
	s_add_i32 m0, s36, 0xc000
	ds_read_b128 v[162:165], v236
	ds_read_b128 v[166:169], v236 offset:1024
	ds_read_b128 v[170:173], v236 offset:2048
	ds_read_b128 v[174:177], v236 offset:3072
	ds_read_b128 v[178:181], v236 offset:4096
	ds_read_b128 v[182:185], v236 offset:5120
	ds_read_b128 v[190:193], v236 offset:6144
	ds_read_b128 v[204:207], v236 offset:7168
	global_load_lds_dwordx4 v[208:209], off
	v_lshl_add_u64 v[208:209], s[4:5], 0, v[200:201]
	s_add_i32 m0, s36, 0xe000
	s_nop 0
	global_load_lds_dwordx4 v[208:209], off
	s_waitcnt vmcnt(8)
	s_waitcnt lgkmcnt(0)
	s_barrier
	s_setprio 1
	s_waitcnt lgkmcnt(0)
	v_mfma_f32_16x16x32_bf16 v[134:137], v[122:125], v[162:165], v[134:137]
	v_mfma_f32_16x16x32_bf16 v[130:133], v[138:141], v[162:165], v[130:133]
	v_mfma_f32_16x16x32_bf16 v[110:113], v[122:125], v[170:173], v[110:113]
	v_mfma_f32_16x16x32_bf16 v[106:109], v[138:141], v[170:173], v[106:109]
	v_mfma_f32_16x16x32_bf16 v[94:97], v[122:125], v[178:181], v[94:97]
	v_mfma_f32_16x16x32_bf16 v[90:93], v[138:141], v[178:181], v[90:93]
	v_mfma_f32_16x16x32_bf16 v[78:81], v[122:125], v[190:193], v[78:81]
	v_mfma_f32_16x16x32_bf16 v[74:77], v[138:141], v[190:193], v[74:77]
	v_mfma_f32_16x16x32_bf16 v[134:137], v[126:129], v[166:169], v[134:137]
	v_mfma_f32_16x16x32_bf16 v[130:133], v[142:145], v[166:169], v[130:133]
	v_mfma_f32_16x16x32_bf16 v[110:113], v[126:129], v[174:177], v[110:113]
	v_mfma_f32_16x16x32_bf16 v[106:109], v[142:145], v[174:177], v[106:109]
	v_mfma_f32_16x16x32_bf16 v[94:97], v[126:129], v[182:185], v[94:97]
	v_mfma_f32_16x16x32_bf16 v[90:93], v[142:145], v[182:185], v[90:93]
	v_mfma_f32_16x16x32_bf16 v[78:81], v[126:129], v[204:207], v[78:81]
	v_mfma_f32_16x16x32_bf16 v[74:77], v[142:145], v[204:207], v[74:77]
	s_setprio 0
	s_setprio 1
	v_mfma_f32_16x16x32_bf16 v[118:121], v[146:149], v[162:165], v[118:121]
	v_mfma_f32_16x16x32_bf16 v[114:117], v[154:157], v[162:165], v[114:117]
	v_mfma_f32_16x16x32_bf16 v[102:105], v[146:149], v[170:173], v[102:105]
	v_mfma_f32_16x16x32_bf16 v[98:101], v[154:157], v[170:173], v[98:101]
	v_mfma_f32_16x16x32_bf16 v[86:89], v[146:149], v[178:181], v[86:89]
	v_mfma_f32_16x16x32_bf16 v[82:85], v[154:157], v[178:181], v[82:85]
	v_mfma_f32_16x16x32_bf16 v[70:73], v[146:149], v[190:193], v[70:73]
	v_mfma_f32_16x16x32_bf16 v[66:69], v[154:157], v[190:193], v[66:69]
	v_mfma_f32_16x16x32_bf16 v[118:121], v[150:153], v[166:169], v[118:121]
	v_mfma_f32_16x16x32_bf16 v[114:117], v[158:161], v[166:169], v[114:117]
	v_mfma_f32_16x16x32_bf16 v[102:105], v[150:153], v[174:177], v[102:105]
	v_mfma_f32_16x16x32_bf16 v[98:101], v[158:161], v[174:177], v[98:101]
	v_mfma_f32_16x16x32_bf16 v[86:89], v[150:153], v[182:185], v[86:89]
	v_mfma_f32_16x16x32_bf16 v[82:85], v[158:161], v[182:185], v[82:85]
	v_mfma_f32_16x16x32_bf16 v[70:73], v[150:153], v[204:207], v[70:73]
	s_barrier
	v_mfma_f32_16x16x32_bf16 v[66:69], v[158:161], v[204:207], v[66:69]
	s_setprio 0
	s_add_i32 s51, s51, s35
	v_lshl_add_u64 v[208:209], s[26:27], 0, v[0:1]
	s_mov_b32 m0, s51
	ds_read_b128 v[162:165], v236 offset:16384
	ds_read_b128 v[166:169], v236 offset:17408
	ds_read_b128 v[170:173], v236 offset:18432
	ds_read_b128 v[174:177], v236 offset:19456
	ds_read_b128 v[178:181], v236 offset:20480
	ds_read_b128 v[182:185], v236 offset:21504
	ds_read_b128 v[190:193], v236 offset:22528
	ds_read_b128 v[204:207], v236 offset:23552
	global_load_lds_dwordx4 v[208:209], off
	s_add_i32 m0, s51, 0x2000
	s_add_u32 s52, s26, 0x80000
	v_lshl_add_u64 v[210:211], s[26:27], 0, v[194:195]
	s_addc_u32 s53, s27, 0
	s_add_i32 s51, s54, s35
	global_load_lds_dwordx4 v[210:211], off
	v_lshl_add_u64 v[212:213], s[52:53], 0, v[0:1]
	s_mov_b32 m0, s51
	v_lshl_add_u64 v[214:215], s[28:29], 0, v[196:197]
	global_load_lds_dwordx4 v[212:213], off
	v_lshl_add_u64 v[212:213], s[52:53], 0, v[194:195]
	s_add_i32 m0, s51, 0x2000
	s_nop 0
	global_load_lds_dwordx4 v[212:213], off
	v_lshl_add_u64 v[212:213], s[28:29], 0, v[198:199]
	s_mov_b32 m0, s36
	s_nop 0
	global_load_lds_dwordx4 v[212:213], off
	s_mov_b32 m0, s37
	s_nop 0
	global_load_lds_dwordx4 v[214:215], off
	s_waitcnt vmcnt(8)
	s_waitcnt lgkmcnt(0)
	s_barrier
; #define PG8_STAGE(bufoff, gbase, voff) do { _Pragma("unroll") for (int _i = 0; _i < 2; ++_i) \
;         __builtin_amdgcn_global_load_lds((const unsigned*)((const char*)(gbase) + (voff)[_i]), (PG8_LAS unsigned*)(lds + (bufoff) + ldsw + _i * 8192), 16, 0, 0); } while (0)
; #define PG8_LDA(dst, b, h) do { _Pragma("unroll") for (int m = 0; m < 4; ++m) _Pragma("unroll") for (int k = 0; k < 2; ++k) dst[m][k] = *(const PG8_LAS bf16x8*)(lds + PG8_SA(b, h) + aoff + m * 2048 + k * 1024); } while (0)
; #define PG8_LDB(dst, b, h) do { _Pragma("unroll") for (int n = 0; n < 2; ++n) _Pragma("unroll") for (int k = 0; k < 2; ++k) dst[n][k] = *(const PG8_LAS bf16x8*)(lds + PG8_SB(b, h) + boff + n * 2048 + k * 1024); } while (0)
; #define PG8_MMA(ai, bj, At, Bt) do { __builtin_amdgcn_s_setprio(1); _Pragma("unroll") for (int m = 0; m < 4; ++m) _Pragma("unroll") for (int n = 0; n < 2; ++n) _Pragma("unroll") for (int k = 0; k < 2; ++k) \
;         acc[ai][bj][m][n] = __builtin_amdgcn_mfma_f32_16x16x32_bf16(Bt[n][k], At[m][k], acc[ai][bj][m][n], 0, 0, 0); __builtin_amdgcn_s_setprio(0); } while (0)
; #define PG8_WAIT_V(n) asm volatile("s_waitcnt vmcnt(" #n ")" ::: "memory")
; #define PG8_WAIT_L(n) asm volatile("s_waitcnt lgkmcnt(" #n ")" ::: "memory")
; #define PG8_BAR __builtin_amdgcn_s_barrier()
; #define PG8_SCHED __builtin_amdgcn_sched_barrier(0)
; template <class Epi, class Sched, bool ALIGN_EPI = false, bool SP2 = false>
; __device__ __forceinline__ void gemm_phase(PG8_LAS unsigned char* lds, const Gemm g, const Sched& S, const Epi& E) {
;     ...
;             PG8_WAIT_V(8); PG8_WAIT_L(0); PG8_BAR; PG8_MMA(1, 0, At, B0); PG8_MMA(1, 1, At, B1); PG8_BAR; PG8_SCHED;
;             PG8_LDB(B0, 1, 0); PG8_LDB(B1, 1, 1); PG8_SCHED; PG8_LDA(At, 1, 0); PG8_STAGE(PG8_SA(0, 1), a2 + hstep, voffA);
;             PG8_WAIT_V(8); PG8_WAIT_L(0); PG8_BAR; PG8_MMA(0, 0, At, B0); PG8_MMA(0, 1, At, B1); PG8_BAR; PG8_SCHED;
	s_setprio 1
	s_waitcnt lgkmcnt(0)
	v_mfma_f32_16x16x32_bf16 v[62:65], v[122:125], v[162:165], v[62:65]
	v_mfma_f32_16x16x32_bf16 v[58:61], v[138:141], v[162:165], v[58:61]
	v_mfma_f32_16x16x32_bf16 v[46:49], v[122:125], v[170:173], v[46:49]
	v_mfma_f32_16x16x32_bf16 v[42:45], v[138:141], v[170:173], v[42:45]
	v_mfma_f32_16x16x32_bf16 v[30:33], v[122:125], v[178:181], v[30:33]
	v_mfma_f32_16x16x32_bf16 v[26:29], v[138:141], v[178:181], v[26:29]
	v_mfma_f32_16x16x32_bf16 v[14:17], v[122:125], v[190:193], v[14:17]
	v_mfma_f32_16x16x32_bf16 v[10:13], v[138:141], v[190:193], v[10:13]
	v_mfma_f32_16x16x32_bf16 v[62:65], v[126:129], v[166:169], v[62:65]
	v_mfma_f32_16x16x32_bf16 v[58:61], v[142:145], v[166:169], v[58:61]
	v_mfma_f32_16x16x32_bf16 v[46:49], v[126:129], v[174:177], v[46:49]
	v_mfma_f32_16x16x32_bf16 v[42:45], v[142:145], v[174:177], v[42:45]
	v_mfma_f32_16x16x32_bf16 v[30:33], v[126:129], v[182:185], v[30:33]
	v_mfma_f32_16x16x32_bf16 v[26:29], v[142:145], v[182:185], v[26:29]
	v_mfma_f32_16x16x32_bf16 v[14:17], v[126:129], v[204:207], v[14:17]
	v_mfma_f32_16x16x32_bf16 v[10:13], v[142:145], v[204:207], v[10:13]
	s_setprio 0
	s_setprio 1
	v_mfma_f32_16x16x32_bf16 v[54:57], v[146:149], v[162:165], v[54:57]
	v_mfma_f32_16x16x32_bf16 v[50:53], v[154:157], v[162:165], v[50:53]
	v_mfma_f32_16x16x32_bf16 v[38:41], v[146:149], v[170:173], v[38:41]
	v_mfma_f32_16x16x32_bf16 v[34:37], v[154:157], v[170:173], v[34:37]
	v_mfma_f32_16x16x32_bf16 v[22:25], v[146:149], v[178:181], v[22:25]
	v_mfma_f32_16x16x32_bf16 v[18:21], v[154:157], v[178:181], v[18:21]
	v_mfma_f32_16x16x32_bf16 v[6:9], v[146:149], v[190:193], v[6:9]
	v_mfma_f32_16x16x32_bf16 v[2:5], v[154:157], v[190:193], v[2:5]
	v_mfma_f32_16x16x32_bf16 v[54:57], v[150:153], v[166:169], v[54:57]
	v_mfma_f32_16x16x32_bf16 v[50:53], v[158:161], v[166:169], v[50:53]
	v_mfma_f32_16x16x32_bf16 v[38:41], v[150:153], v[174:177], v[38:41]
	v_mfma_f32_16x16x32_bf16 v[34:37], v[158:161], v[174:177], v[34:37]
	v_mfma_f32_16x16x32_bf16 v[22:25], v[150:153], v[182:185], v[22:25]
	v_mfma_f32_16x16x32_bf16 v[18:21], v[158:161], v[182:185], v[18:21]
	v_mfma_f32_16x16x32_bf16 v[6:9], v[150:153], v[204:207], v[6:9]
	s_barrier
	v_mfma_f32_16x16x32_bf16 v[2:5], v[158:161], v[204:207], v[2:5]
	s_setprio 0
	s_add_i32 s51, 0, 0x18000
	s_add_i32 s52, 0, 0x1c000
	v_add_u32_e32 v142, s51, v232
	v_add_u32_e32 v158, s52, v232
	ds_read_b128 v[122:125], v142
	ds_read_b128 v[126:129], v142 offset:1024
	ds_read_b128 v[138:141], v142 offset:2048
	ds_read_b128 v[142:145], v142 offset:3072
	ds_read_b128 v[146:149], v158
	ds_read_b128 v[150:153], v158 offset:1024
	ds_read_b128 v[154:157], v158 offset:2048
	ds_read_b128 v[158:161], v158 offset:3072
	s_add_u32 s28, s28, 0x80000
	s_addc_u32 s29, s29, 0
	s_mov_b32 m0, s38
	v_lshl_add_u64 v[216:217], s[28:29], 0, v[198:199]
	ds_read_b128 v[162:165], v236 offset:32768
	ds_read_b128 v[166:169], v236 offset:33792
	ds_read_b128 v[170:173], v236 offset:34816
	ds_read_b128 v[174:177], v236 offset:35840
	ds_read_b128 v[178:181], v236 offset:36864
	ds_read_b128 v[182:185], v236 offset:37888
	ds_read_b128 v[190:193], v236 offset:38912
	ds_read_b128 v[204:207], v236 offset:39936
	global_load_lds_dwordx4 v[216:217], off
	v_lshl_add_u64 v[216:217], s[28:29], 0, v[196:197]
	s_mov_b32 m0, s39
	s_nop 0
	global_load_lds_dwordx4 v[216:217], off
	s_waitcnt vmcnt(8)
	s_waitcnt lgkmcnt(0)
	s_barrier
	s_setprio 1
	s_waitcnt lgkmcnt(0)
	v_mfma_f32_16x16x32_bf16 v[134:137], v[122:125], v[162:165], v[134:137]
	v_mfma_f32_16x16x32_bf16 v[130:133], v[138:141], v[162:165], v[130:133]
	v_mfma_f32_16x16x32_bf16 v[110:113], v[122:125], v[170:173], v[110:113]
	v_mfma_f32_16x16x32_bf16 v[106:109], v[138:141], v[170:173], v[106:109]
	v_mfma_f32_16x16x32_bf16 v[94:97], v[122:125], v[178:181], v[94:97]
	v_mfma_f32_16x16x32_bf16 v[90:93], v[138:141], v[178:181], v[90:93]
	v_mfma_f32_16x16x32_bf16 v[78:81], v[122:125], v[190:193], v[78:81]
	v_mfma_f32_16x16x32_bf16 v[74:77], v[138:141], v[190:193], v[74:77]
	v_mfma_f32_16x16x32_bf16 v[134:137], v[126:129], v[166:169], v[134:137]
	v_mfma_f32_16x16x32_bf16 v[130:133], v[142:145], v[166:169], v[130:133]
	v_mfma_f32_16x16x32_bf16 v[110:113], v[126:129], v[174:177], v[110:113]
	v_mfma_f32_16x16x32_bf16 v[106:109], v[142:145], v[174:177], v[106:109]
	v_mfma_f32_16x16x32_bf16 v[94:97], v[126:129], v[182:185], v[94:97]
	v_mfma_f32_16x16x32_bf16 v[90:93], v[142:145], v[182:185], v[90:93]
	v_mfma_f32_16x16x32_bf16 v[78:81], v[126:129], v[204:207], v[78:81]
	v_mfma_f32_16x16x32_bf16 v[74:77], v[142:145], v[204:207], v[74:77]
	s_setprio 0
	s_setprio 1
	v_mfma_f32_16x16x32_bf16 v[118:121], v[146:149], v[162:165], v[118:121]
	v_mfma_f32_16x16x32_bf16 v[114:117], v[154:157], v[162:165], v[114:117]
	v_mfma_f32_16x16x32_bf16 v[102:105], v[146:149], v[170:173], v[102:105]
	v_mfma_f32_16x16x32_bf16 v[98:101], v[154:157], v[170:173], v[98:101]
	v_mfma_f32_16x16x32_bf16 v[86:89], v[146:149], v[178:181], v[86:89]
	v_mfma_f32_16x16x32_bf16 v[82:85], v[154:157], v[178:181], v[82:85]
	v_mfma_f32_16x16x32_bf16 v[70:73], v[146:149], v[190:193], v[70:73]
	v_mfma_f32_16x16x32_bf16 v[66:69], v[154:157], v[190:193], v[66:69]
	v_mfma_f32_16x16x32_bf16 v[118:121], v[150:153], v[166:169], v[118:121]
	v_mfma_f32_16x16x32_bf16 v[114:117], v[158:161], v[166:169], v[114:117]
	v_mfma_f32_16x16x32_bf16 v[102:105], v[150:153], v[174:177], v[102:105]
	v_mfma_f32_16x16x32_bf16 v[98:101], v[158:161], v[174:177], v[98:101]
	v_mfma_f32_16x16x32_bf16 v[86:89], v[150:153], v[182:185], v[86:89]
	v_mfma_f32_16x16x32_bf16 v[82:85], v[158:161], v[182:185], v[82:85]
	v_mfma_f32_16x16x32_bf16 v[70:73], v[150:153], v[204:207], v[70:73]
	s_barrier
; #define PG8_STAGE(bufoff, gbase, voff) do { _Pragma("unroll") for (int _i = 0; _i < 2; ++_i) \
;         __builtin_amdgcn_global_load_lds((const unsigned*)((const char*)(gbase) + (voff)[_i]), (PG8_LAS unsigned*)(lds + (bufoff) + ldsw + _i * 8192), 16, 0, 0); } while (0)
; #define PG8_LDA(dst, b, h) do { _Pragma("unroll") for (int m = 0; m < 4; ++m) _Pragma("unroll") for (int k = 0; k < 2; ++k) dst[m][k] = *(const PG8_LAS bf16x8*)(lds + PG8_SA(b, h) + aoff + m * 2048 + k * 1024); } while (0)
; #define PG8_MMA(ai, bj, At, Bt) do { __builtin_amdgcn_s_setprio(1); _Pragma("unroll") for (int m = 0; m < 4; ++m) _Pragma("unroll") for (int n = 0; n < 2; ++n) _Pragma("unroll") for (int k = 0; k < 2; ++k) \
;         acc[ai][bj][m][n] = __builtin_amdgcn_mfma_f32_16x16x32_bf16(Bt[n][k], At[m][k], acc[ai][bj][m][n], 0, 0, 0); __builtin_amdgcn_s_setprio(0); } while (0)
; #define PG8_WAIT_V(n) asm volatile("s_waitcnt vmcnt(" #n ")" ::: "memory")
; #define PG8_WAIT_L(n) asm volatile("s_waitcnt lgkmcnt(" #n ")" ::: "memory")
; #define PG8_BAR __builtin_amdgcn_s_barrier()
; #define PG8_SCHED __builtin_amdgcn_sched_barrier(0)
; template <class Epi, class Sched, bool ALIGN_EPI = false, bool SP2 = false>
; __device__ __forceinline__ void gemm_phase(PG8_LAS unsigned char* lds, const Gemm g, const Sched& S, const Epi& E) {
;     ...
;         for (int t = 0; t < nt; t += 2) {
;             const bool last = (t == nt - 2);
;     ...
;             PG8_WAIT_V(8); PG8_WAIT_L(0); PG8_BAR; PG8_MMA(0, 0, At, B0); PG8_MMA(0, 1, At, B1); PG8_BAR; PG8_SCHED;
;             PG8_LDA(At, 1, 1); PG8_STAGE(PG8_SB(1, 0), b3, voffB); PG8_STAGE(PG8_SB(1, 1), b3 + hstep, voffB); PG8_STAGE(PG8_SA(1, 0), a3, voffA);
;             PG8_WAIT_V(8); PG8_WAIT_L(0); PG8_BAR; PG8_MMA(1, 0, At, B0); PG8_MMA(1, 1, At, B1); PG8_BAR; PG8_SCHED;
	v_mfma_f32_16x16x32_bf16 v[66:69], v[158:161], v[204:207], v[66:69]
	s_setprio 0
	s_add_i32 s28, s51, s35
	v_lshl_add_u64 v[208:209], v[208:209], 0, s[56:57]
	s_mov_b32 m0, s28
	ds_read_b128 v[162:165], v236 offset:49152
	ds_read_b128 v[166:169], v236 offset:50176
	ds_read_b128 v[170:173], v236 offset:51200
	ds_read_b128 v[174:177], v236 offset:52224
	ds_read_b128 v[178:181], v236 offset:53248
	ds_read_b128 v[182:185], v236 offset:54272
	ds_read_b128 v[190:193], v236 offset:55296
	ds_read_b128 v[204:207], v236 offset:56320
	global_load_lds_dwordx4 v[208:209], off
	s_add_i32 m0, s28, 0x2000
	s_add_u32 s26, s26, 0x80080
	v_lshl_add_u64 v[208:209], v[210:211], 0, s[56:57]
	s_addc_u32 s27, s27, 0
	s_add_i32 s28, s52, s35
	global_load_lds_dwordx4 v[208:209], off
	v_lshl_add_u64 v[208:209], s[26:27], 0, v[0:1]
	s_mov_b32 m0, s28
	s_nop 0
	global_load_lds_dwordx4 v[208:209], off
	v_lshl_add_u64 v[208:209], s[26:27], 0, v[194:195]
	s_add_i32 m0, s28, 0x2000
	s_nop 0
	global_load_lds_dwordx4 v[208:209], off
	v_lshl_add_u64 v[208:209], v[212:213], 0, s[56:57]
	s_mov_b32 m0, s41
	s_nop 0
	global_load_lds_dwordx4 v[208:209], off
	v_lshl_add_u64 v[208:209], v[214:215], 0, s[56:57]
	s_mov_b32 m0, s42
	s_nop 0
	global_load_lds_dwordx4 v[208:209], off
	s_waitcnt vmcnt(8)
	s_waitcnt lgkmcnt(0)
	s_barrier
	s_setprio 1
	s_waitcnt lgkmcnt(0)
	v_mfma_f32_16x16x32_bf16 v[62:65], v[122:125], v[162:165], v[62:65]
	v_mfma_f32_16x16x32_bf16 v[58:61], v[138:141], v[162:165], v[58:61]
	v_mfma_f32_16x16x32_bf16 v[46:49], v[122:125], v[170:173], v[46:49]
	v_mfma_f32_16x16x32_bf16 v[42:45], v[138:141], v[170:173], v[42:45]
	v_mfma_f32_16x16x32_bf16 v[30:33], v[122:125], v[178:181], v[30:33]
	v_mfma_f32_16x16x32_bf16 v[26:29], v[138:141], v[178:181], v[26:29]
	v_mfma_f32_16x16x32_bf16 v[14:17], v[122:125], v[190:193], v[14:17]
	v_mfma_f32_16x16x32_bf16 v[10:13], v[138:141], v[190:193], v[10:13]
	v_mfma_f32_16x16x32_bf16 v[62:65], v[126:129], v[166:169], v[62:65]
	v_mfma_f32_16x16x32_bf16 v[58:61], v[142:145], v[166:169], v[58:61]
	v_mfma_f32_16x16x32_bf16 v[46:49], v[126:129], v[174:177], v[46:49]
	v_mfma_f32_16x16x32_bf16 v[42:45], v[142:145], v[174:177], v[42:45]
	v_mfma_f32_16x16x32_bf16 v[30:33], v[126:129], v[182:185], v[30:33]
	v_mfma_f32_16x16x32_bf16 v[26:29], v[142:145], v[182:185], v[26:29]
	v_mfma_f32_16x16x32_bf16 v[14:17], v[126:129], v[204:207], v[14:17]
	v_mfma_f32_16x16x32_bf16 v[10:13], v[142:145], v[204:207], v[10:13]
	s_setprio 0
	s_setprio 1
	v_mfma_f32_16x16x32_bf16 v[54:57], v[146:149], v[162:165], v[54:57]
	v_mfma_f32_16x16x32_bf16 v[50:53], v[154:157], v[162:165], v[50:53]
	v_mfma_f32_16x16x32_bf16 v[38:41], v[146:149], v[170:173], v[38:41]
	v_mfma_f32_16x16x32_bf16 v[34:37], v[154:157], v[170:173], v[34:37]
	v_mfma_f32_16x16x32_bf16 v[22:25], v[146:149], v[178:181], v[22:25]
	v_mfma_f32_16x16x32_bf16 v[18:21], v[154:157], v[178:181], v[18:21]
	v_mfma_f32_16x16x32_bf16 v[6:9], v[146:149], v[190:193], v[6:9]
	v_mfma_f32_16x16x32_bf16 v[2:5], v[154:157], v[190:193], v[2:5]
	v_mfma_f32_16x16x32_bf16 v[54:57], v[150:153], v[166:169], v[54:57]
	v_mfma_f32_16x16x32_bf16 v[50:53], v[158:161], v[166:169], v[50:53]
	v_mfma_f32_16x16x32_bf16 v[38:41], v[150:153], v[174:177], v[38:41]
	v_mfma_f32_16x16x32_bf16 v[34:37], v[158:161], v[174:177], v[34:37]
	v_mfma_f32_16x16x32_bf16 v[22:25], v[150:153], v[182:185], v[22:25]
	v_mfma_f32_16x16x32_bf16 v[18:21], v[158:161], v[182:185], v[18:21]
	v_mfma_f32_16x16x32_bf16 v[6:9], v[150:153], v[204:207], v[6:9]
	s_barrier
	v_mfma_f32_16x16x32_bf16 v[2:5], v[158:161], v[204:207], v[2:5]
	s_setprio 0
	s_add_i32 s50, s50, 2
	s_add_u32 s48, s48, 0x100
	s_addc_u32 s49, s49, 0
	s_add_u32 s4, s4, 0x100
	s_addc_u32 s5, s5, 0
	s_cmp_gt_u32 s50, 29
	s_cbranch_scc0 .LBB0_1182
	s_and_b64 vcc, exec, s[16:17]
	s_cbranch_vccz .LBB0_1185
	s_barrier
